# scalar-base LDS-DMA addressing also in the out_proj K-loop (14 of its 16 pieces)
# baseline (speedup 1.0000x reference)
.LBB0_504:
	s_add_u32 s10, s16, s44
	s_addc_u32 s11, s17, s45
	s_add_u32 s10, s10, 0x100
	s_addc_u32 s11, s11, 0
	s_add_u32 s18, s13, s44
	s_addc_u32 s19, s14, s45
	s_cmpk_eq_i32 s44, 0xb00
	s_cselect_b32 s25, s5, s11
	s_cselect_b32 s24, s4, s10
	s_cselect_b32 s23, s7, s19
	s_cselect_b32 s22, s6, s18
	s_add_i32 s10, 0, 0x10000
	v_add_u32_e32 v0, s10, v208
	s_add_i32 s18, 0, 0x14000
	ds_read_b128 v[162:165], v0
	ds_read_b128 v[166:169], v0 offset:1024
	ds_read_b128 v[170:173], v0 offset:2048
	ds_read_b128 v[174:177], v0 offset:3072
	v_add_u32_e32 v0, s18, v208
	ds_read_b128 v[178:181], v0
	ds_read_b128 v[182:185], v0 offset:1024
	ds_read_b128 v[212:215], v0 offset:2048
	ds_read_b128 v[216:219], v0 offset:3072
	v_lshl_add_u64 v[0:1], v[158:159], 0, s[44:45]
	s_add_i32 m0, s47, 0xc000
	ds_read_b128 v[220:223], v211
	ds_read_b128 v[224:227], v211 offset:1024
	ds_read_b128 v[228:231], v211 offset:2048
	ds_read_b128 v[232:235], v211 offset:3072
	ds_read_b128 v[236:239], v211 offset:4096
	ds_read_b128 v[240:243], v211 offset:5120
	ds_read_b128 v[244:247], v211 offset:6144
	ds_read_b128 v[248:251], v211 offset:7168
	global_load_lds_dwordx4 v[0:1], off
	v_lshl_add_u64 v[0:1], v[160:161], 0, s[44:45]
	s_add_i32 m0, s47, 0xe000
	s_nop 0
	global_load_lds_dwordx4 v[0:1], off
	s_waitcnt vmcnt(8)
	s_waitcnt lgkmcnt(0)
	s_barrier
	s_setprio 1
	s_waitcnt lgkmcnt(0)
	v_mfma_f32_16x16x32_bf16 v[128:131], v[162:165], v[220:223], v[128:131]
	v_mfma_f32_16x16x32_bf16 v[124:127], v[170:173], v[220:223], v[124:127]
	v_mfma_f32_16x16x32_bf16 v[112:115], v[162:165], v[228:231], v[112:115]
	v_mfma_f32_16x16x32_bf16 v[108:111], v[170:173], v[228:231], v[108:111]
	v_mfma_f32_16x16x32_bf16 v[96:99], v[162:165], v[236:239], v[96:99]
	v_mfma_f32_16x16x32_bf16 v[92:95], v[170:173], v[236:239], v[92:95]
	v_mfma_f32_16x16x32_bf16 v[80:83], v[162:165], v[244:247], v[80:83]
	v_mfma_f32_16x16x32_bf16 v[76:79], v[170:173], v[244:247], v[76:79]
	v_mfma_f32_16x16x32_bf16 v[128:131], v[166:169], v[224:227], v[128:131]
	v_mfma_f32_16x16x32_bf16 v[124:127], v[174:177], v[224:227], v[124:127]
	v_mfma_f32_16x16x32_bf16 v[112:115], v[166:169], v[232:235], v[112:115]
	v_mfma_f32_16x16x32_bf16 v[108:111], v[174:177], v[232:235], v[108:111]
	v_mfma_f32_16x16x32_bf16 v[96:99], v[166:169], v[240:243], v[96:99]
	v_mfma_f32_16x16x32_bf16 v[92:95], v[174:177], v[240:243], v[92:95]
	v_mfma_f32_16x16x32_bf16 v[80:83], v[166:169], v[248:251], v[80:83]
	v_mfma_f32_16x16x32_bf16 v[76:79], v[174:177], v[248:251], v[76:79]
	s_setprio 0
	s_setprio 1
	v_mfma_f32_16x16x32_bf16 v[120:123], v[178:181], v[220:223], v[120:123]
	v_mfma_f32_16x16x32_bf16 v[116:119], v[212:215], v[220:223], v[116:119]
	v_mfma_f32_16x16x32_bf16 v[104:107], v[178:181], v[228:231], v[104:107]
	v_mfma_f32_16x16x32_bf16 v[100:103], v[212:215], v[228:231], v[100:103]
	v_mfma_f32_16x16x32_bf16 v[88:91], v[178:181], v[236:239], v[88:91]
	v_mfma_f32_16x16x32_bf16 v[84:87], v[212:215], v[236:239], v[84:87]
	v_mfma_f32_16x16x32_bf16 v[72:75], v[178:181], v[244:247], v[72:75]
	v_mfma_f32_16x16x32_bf16 v[68:71], v[212:215], v[244:247], v[68:71]
	v_mfma_f32_16x16x32_bf16 v[120:123], v[182:185], v[224:227], v[120:123]
	v_mfma_f32_16x16x32_bf16 v[116:119], v[216:219], v[224:227], v[116:119]
	v_mfma_f32_16x16x32_bf16 v[104:107], v[182:185], v[232:235], v[104:107]
	v_mfma_f32_16x16x32_bf16 v[100:103], v[216:219], v[232:235], v[100:103]
	v_mfma_f32_16x16x32_bf16 v[88:91], v[182:185], v[240:243], v[88:91]
	v_mfma_f32_16x16x32_bf16 v[84:87], v[216:219], v[240:243], v[84:87]
	v_mfma_f32_16x16x32_bf16 v[72:75], v[182:185], v[248:251], v[72:75]
	v_mfma_f32_16x16x32_bf16 v[68:71], v[216:219], v[248:251], v[68:71]
	s_setprio 0
	s_barrier
	s_add_i32 s10, s10, s46
	s_mov_b32 m0, s10
	ds_read_b128 v[220:223], v211 offset:16384
	ds_read_b128 v[224:227], v211 offset:17408
	ds_read_b128 v[228:231], v211 offset:18432
	ds_read_b128 v[232:235], v211 offset:19456
	ds_read_b128 v[236:239], v211 offset:20480
	ds_read_b128 v[240:243], v211 offset:21504
	ds_read_b128 v[244:247], v211 offset:22528
	ds_read_b128 v[248:251], v211 offset:23552
	global_load_lds_dwordx4 v140, s[22:23]
	s_add_i32 m0, s10, 0x2000
	s_add_u32 s10, s22, 0x60000
	s_addc_u32 s11, s23, 0
	s_add_i32 s18, s18, s46
	global_load_lds_dwordx4 v142, s[22:23]
	s_mov_b32 m0, s18
	s_nop 0
	global_load_lds_dwordx4 v140, s[10:11]
	s_add_i32 m0, s18, 0x2000
	s_nop 0
	global_load_lds_dwordx4 v142, s[10:11]
	s_mov_b32 m0, s47
	s_nop 0
	global_load_lds_dwordx4 v140, s[24:25]
	s_mov_b32 m0, s48
	s_nop 0
	global_load_lds_dwordx4 v142, s[24:25]
	s_waitcnt vmcnt(8)
	s_waitcnt lgkmcnt(0)
	s_barrier
	s_setprio 1
	s_waitcnt lgkmcnt(0)
	v_mfma_f32_16x16x32_bf16 v[64:67], v[162:165], v[220:223], v[64:67]
	v_mfma_f32_16x16x32_bf16 v[60:63], v[170:173], v[220:223], v[60:63]
	v_mfma_f32_16x16x32_bf16 v[48:51], v[162:165], v[228:231], v[48:51]
	v_mfma_f32_16x16x32_bf16 v[44:47], v[170:173], v[228:231], v[44:47]
	v_mfma_f32_16x16x32_bf16 v[32:35], v[162:165], v[236:239], v[32:35]
	v_mfma_f32_16x16x32_bf16 v[28:31], v[170:173], v[236:239], v[28:31]
	v_mfma_f32_16x16x32_bf16 v[16:19], v[162:165], v[244:247], v[16:19]
	v_mfma_f32_16x16x32_bf16 v[12:15], v[170:173], v[244:247], v[12:15]
	v_mfma_f32_16x16x32_bf16 v[64:67], v[166:169], v[224:227], v[64:67]
	v_mfma_f32_16x16x32_bf16 v[60:63], v[174:177], v[224:227], v[60:63]
	v_mfma_f32_16x16x32_bf16 v[48:51], v[166:169], v[232:235], v[48:51]
	v_mfma_f32_16x16x32_bf16 v[44:47], v[174:177], v[232:235], v[44:47]
	v_mfma_f32_16x16x32_bf16 v[32:35], v[166:169], v[240:243], v[32:35]
	v_mfma_f32_16x16x32_bf16 v[28:31], v[174:177], v[240:243], v[28:31]
	v_mfma_f32_16x16x32_bf16 v[16:19], v[166:169], v[248:251], v[16:19]
	v_mfma_f32_16x16x32_bf16 v[12:15], v[174:177], v[248:251], v[12:15]
	s_setprio 0
	s_setprio 1
	v_mfma_f32_16x16x32_bf16 v[56:59], v[178:181], v[220:223], v[56:59]
	v_mfma_f32_16x16x32_bf16 v[52:55], v[212:215], v[220:223], v[52:55]
	v_mfma_f32_16x16x32_bf16 v[40:43], v[178:181], v[228:231], v[40:43]
	v_mfma_f32_16x16x32_bf16 v[36:39], v[212:215], v[228:231], v[36:39]
	v_mfma_f32_16x16x32_bf16 v[24:27], v[178:181], v[236:239], v[24:27]
	v_mfma_f32_16x16x32_bf16 v[20:23], v[212:215], v[236:239], v[20:23]
	v_mfma_f32_16x16x32_bf16 v[8:11], v[178:181], v[244:247], v[8:11]
	v_mfma_f32_16x16x32_bf16 v[4:7], v[212:215], v[244:247], v[4:7]
	v_mfma_f32_16x16x32_bf16 v[56:59], v[182:185], v[224:227], v[56:59]
	v_mfma_f32_16x16x32_bf16 v[52:55], v[216:219], v[224:227], v[52:55]
	v_mfma_f32_16x16x32_bf16 v[40:43], v[182:185], v[232:235], v[40:43]
	v_mfma_f32_16x16x32_bf16 v[36:39], v[216:219], v[232:235], v[36:39]
	v_mfma_f32_16x16x32_bf16 v[24:27], v[182:185], v[240:243], v[24:27]
	v_mfma_f32_16x16x32_bf16 v[20:23], v[216:219], v[240:243], v[20:23]
	v_mfma_f32_16x16x32_bf16 v[8:11], v[182:185], v[248:251], v[8:11]
	v_mfma_f32_16x16x32_bf16 v[4:7], v[216:219], v[248:251], v[4:7]
	s_setprio 0
	s_barrier
	s_add_i32 s18, 0, 0x18000
	v_add_u32_e32 v2, s18, v208
	s_add_i32 s19, 0, 0x1c000
	ds_read_b128 v[162:165], v2
	ds_read_b128 v[166:169], v2 offset:1024
	ds_read_b128 v[170:173], v2 offset:2048
	ds_read_b128 v[174:177], v2 offset:3072
	v_add_u32_e32 v2, s19, v208
	ds_read_b128 v[178:181], v2
	ds_read_b128 v[182:185], v2 offset:1024
	ds_read_b128 v[212:215], v2 offset:2048
	ds_read_b128 v[216:219], v2 offset:3072
	s_add_u32 s10, s24, 0x60000
	s_addc_u32 s11, s25, 0
	s_mov_b32 m0, s49
	ds_read_b128 v[220:223], v211 offset:32768
	ds_read_b128 v[224:227], v211 offset:33792
	ds_read_b128 v[228:231], v211 offset:34816
	ds_read_b128 v[232:235], v211 offset:35840
	ds_read_b128 v[236:239], v211 offset:36864
	ds_read_b128 v[240:243], v211 offset:37888
	ds_read_b128 v[244:247], v211 offset:38912
	ds_read_b128 v[248:251], v211 offset:39936
	global_load_lds_dwordx4 v140, s[10:11]
	s_mov_b32 m0, s50
	s_nop 0
	global_load_lds_dwordx4 v142, s[10:11]
	s_waitcnt vmcnt(8)
	s_waitcnt lgkmcnt(0)
	s_barrier
	s_setprio 1
	s_waitcnt lgkmcnt(0)
	v_mfma_f32_16x16x32_bf16 v[128:131], v[162:165], v[220:223], v[128:131]
	v_mfma_f32_16x16x32_bf16 v[124:127], v[170:173], v[220:223], v[124:127]
	v_mfma_f32_16x16x32_bf16 v[112:115], v[162:165], v[228:231], v[112:115]
	v_mfma_f32_16x16x32_bf16 v[108:111], v[170:173], v[228:231], v[108:111]
	v_mfma_f32_16x16x32_bf16 v[96:99], v[162:165], v[236:239], v[96:99]
	v_mfma_f32_16x16x32_bf16 v[92:95], v[170:173], v[236:239], v[92:95]
	v_mfma_f32_16x16x32_bf16 v[80:83], v[162:165], v[244:247], v[80:83]
	v_mfma_f32_16x16x32_bf16 v[76:79], v[170:173], v[244:247], v[76:79]
	v_mfma_f32_16x16x32_bf16 v[128:131], v[166:169], v[224:227], v[128:131]
	v_mfma_f32_16x16x32_bf16 v[124:127], v[174:177], v[224:227], v[124:127]
	v_mfma_f32_16x16x32_bf16 v[112:115], v[166:169], v[232:235], v[112:115]
	v_mfma_f32_16x16x32_bf16 v[108:111], v[174:177], v[232:235], v[108:111]
	v_mfma_f32_16x16x32_bf16 v[96:99], v[166:169], v[240:243], v[96:99]
	v_mfma_f32_16x16x32_bf16 v[92:95], v[174:177], v[240:243], v[92:95]
	v_mfma_f32_16x16x32_bf16 v[80:83], v[166:169], v[248:251], v[80:83]
	v_mfma_f32_16x16x32_bf16 v[76:79], v[174:177], v[248:251], v[76:79]
	s_setprio 0
	s_setprio 1
	v_mfma_f32_16x16x32_bf16 v[120:123], v[178:181], v[220:223], v[120:123]
	v_mfma_f32_16x16x32_bf16 v[116:119], v[212:215], v[220:223], v[116:119]
	v_mfma_f32_16x16x32_bf16 v[104:107], v[178:181], v[228:231], v[104:107]
	v_mfma_f32_16x16x32_bf16 v[100:103], v[212:215], v[228:231], v[100:103]
	v_mfma_f32_16x16x32_bf16 v[88:91], v[178:181], v[236:239], v[88:91]
	v_mfma_f32_16x16x32_bf16 v[84:87], v[212:215], v[236:239], v[84:87]
	v_mfma_f32_16x16x32_bf16 v[72:75], v[178:181], v[244:247], v[72:75]
	v_mfma_f32_16x16x32_bf16 v[68:71], v[212:215], v[244:247], v[68:71]
	v_mfma_f32_16x16x32_bf16 v[120:123], v[182:185], v[224:227], v[120:123]
	v_mfma_f32_16x16x32_bf16 v[116:119], v[216:219], v[224:227], v[116:119]
	v_mfma_f32_16x16x32_bf16 v[104:107], v[182:185], v[232:235], v[104:107]
	v_mfma_f32_16x16x32_bf16 v[100:103], v[216:219], v[232:235], v[100:103]
	v_mfma_f32_16x16x32_bf16 v[88:91], v[182:185], v[240:243], v[88:91]
	v_mfma_f32_16x16x32_bf16 v[84:87], v[216:219], v[240:243], v[84:87]
	v_mfma_f32_16x16x32_bf16 v[72:75], v[182:185], v[248:251], v[72:75]
	v_mfma_f32_16x16x32_bf16 v[68:71], v[216:219], v[248:251], v[68:71]
	s_setprio 0
	s_barrier
	s_add_i32 s10, s18, s46
	s_add_u32 s100, s22, 0x80
	s_addc_u32 s101, s23, 0
	s_mov_b32 m0, s10
	ds_read_b128 v[220:223], v211 offset:49152
	ds_read_b128 v[224:227], v211 offset:50176
	ds_read_b128 v[228:231], v211 offset:51200
	ds_read_b128 v[232:235], v211 offset:52224
	ds_read_b128 v[236:239], v211 offset:53248
	ds_read_b128 v[240:243], v211 offset:54272
	ds_read_b128 v[244:247], v211 offset:55296
	ds_read_b128 v[248:251], v211 offset:56320
	global_load_lds_dwordx4 v140, s[100:101]
	s_add_i32 m0, s10, 0x2000
	s_add_u32 s10, s22, 0x60080
	s_addc_u32 s11, s23, 0
	s_add_i32 s18, s19, s46
	global_load_lds_dwordx4 v142, s[100:101]
	s_mov_b32 m0, s18
	s_nop 0
	global_load_lds_dwordx4 v140, s[10:11]
	s_add_i32 m0, s18, 0x2000
	s_nop 0
	global_load_lds_dwordx4 v142, s[10:11]
	s_add_u32 s100, s24, 0x80
	s_addc_u32 s101, s25, 0
	s_mov_b32 m0, s52
	s_nop 0
	global_load_lds_dwordx4 v140, s[100:101]
	s_mov_b32 m0, s53
	s_nop 0
	global_load_lds_dwordx4 v142, s[100:101]
	s_waitcnt vmcnt(8)
	s_waitcnt lgkmcnt(0)
	s_barrier
	s_setprio 1
	s_waitcnt lgkmcnt(0)
	v_mfma_f32_16x16x32_bf16 v[64:67], v[162:165], v[220:223], v[64:67]
	v_mfma_f32_16x16x32_bf16 v[60:63], v[170:173], v[220:223], v[60:63]
	v_mfma_f32_16x16x32_bf16 v[48:51], v[162:165], v[228:231], v[48:51]
	v_mfma_f32_16x16x32_bf16 v[44:47], v[170:173], v[228:231], v[44:47]
	v_mfma_f32_16x16x32_bf16 v[32:35], v[162:165], v[236:239], v[32:35]
	v_mfma_f32_16x16x32_bf16 v[28:31], v[170:173], v[236:239], v[28:31]
	v_mfma_f32_16x16x32_bf16 v[16:19], v[162:165], v[244:247], v[16:19]
	v_mfma_f32_16x16x32_bf16 v[12:15], v[170:173], v[244:247], v[12:15]
	v_mfma_f32_16x16x32_bf16 v[64:67], v[166:169], v[224:227], v[64:67]
	v_mfma_f32_16x16x32_bf16 v[60:63], v[174:177], v[224:227], v[60:63]
	v_mfma_f32_16x16x32_bf16 v[48:51], v[166:169], v[232:235], v[48:51]
	v_mfma_f32_16x16x32_bf16 v[44:47], v[174:177], v[232:235], v[44:47]
	v_mfma_f32_16x16x32_bf16 v[32:35], v[166:169], v[240:243], v[32:35]
	v_mfma_f32_16x16x32_bf16 v[28:31], v[174:177], v[240:243], v[28:31]
	v_mfma_f32_16x16x32_bf16 v[16:19], v[166:169], v[248:251], v[16:19]
	v_mfma_f32_16x16x32_bf16 v[12:15], v[174:177], v[248:251], v[12:15]
	s_setprio 0
	s_setprio 1
	v_mfma_f32_16x16x32_bf16 v[56:59], v[178:181], v[220:223], v[56:59]
	v_mfma_f32_16x16x32_bf16 v[52:55], v[212:215], v[220:223], v[52:55]
	v_mfma_f32_16x16x32_bf16 v[40:43], v[178:181], v[228:231], v[40:43]
	v_mfma_f32_16x16x32_bf16 v[36:39], v[212:215], v[228:231], v[36:39]
	v_mfma_f32_16x16x32_bf16 v[24:27], v[178:181], v[236:239], v[24:27]
	v_mfma_f32_16x16x32_bf16 v[20:23], v[212:215], v[236:239], v[20:23]
	v_mfma_f32_16x16x32_bf16 v[8:11], v[178:181], v[244:247], v[8:11]
	v_mfma_f32_16x16x32_bf16 v[4:7], v[212:215], v[244:247], v[4:7]
	v_mfma_f32_16x16x32_bf16 v[56:59], v[182:185], v[224:227], v[56:59]
	v_mfma_f32_16x16x32_bf16 v[52:55], v[216:219], v[224:227], v[52:55]
	v_mfma_f32_16x16x32_bf16 v[40:43], v[182:185], v[232:235], v[40:43]
	v_mfma_f32_16x16x32_bf16 v[36:39], v[216:219], v[232:235], v[36:39]
	v_mfma_f32_16x16x32_bf16 v[24:27], v[182:185], v[240:243], v[24:27]
	v_mfma_f32_16x16x32_bf16 v[20:23], v[216:219], v[240:243], v[20:23]
	v_mfma_f32_16x16x32_bf16 v[8:11], v[182:185], v[248:251], v[8:11]
	v_mfma_f32_16x16x32_bf16 v[4:7], v[216:219], v[248:251], v[4:7]
	s_setprio 0
	s_barrier
	s_add_i32 s10, s15, 2
	s_add_u32 s44, s44, 0x100
	s_addc_u32 s45, s45, 0
	s_cmp_gt_u32 s15, 21
	s_cbranch_scc1 .LBB0_513
	s_mov_b32 s15, s10
	s_cmp_lt_i32 s15, 16
	s_cbranch_scc1 .LBB0_490
